# v1 + first 2 MFMAs of each K-loop phase issued before the leading barrier
# speedup vs baseline: 1.0077x; 1.0049x over previous
; #define PG8_STAGE(bufoff, gbase, voff) do { _Pragma("unroll") for (int _i = 0; _i < 2; ++_i) \
;         __builtin_amdgcn_global_load_lds((const unsigned*)((const char*)(gbase) + (voff)[_i]), (PG8_LAS unsigned*)(lds + (bufoff) + ldsw + _i * 8192), 16, 0, 0); } while (0)
; #define PG8_LDA(dst, b, h) do { _Pragma("unroll") for (int m = 0; m < 4; ++m) _Pragma("unroll") for (int k = 0; k < 2; ++k) dst[m][k] = *(const PG8_LAS bf16x8*)(lds + PG8_SA(b, h) + aoff + m * 2048 + k * 1024); } while (0)
; #define PG8_LDB(dst, b, h) do { _Pragma("unroll") for (int n = 0; n < 2; ++n) _Pragma("unroll") for (int k = 0; k < 2; ++k) dst[n][k] = *(const PG8_LAS bf16x8*)(lds + PG8_SB(b, h) + boff + n * 2048 + k * 1024); } while (0)
; #define PG8_WAIT_V(n) asm volatile("s_waitcnt vmcnt(" #n ")" ::: "memory")
; #define PG8_WAIT_L(n) asm volatile("s_waitcnt lgkmcnt(" #n ")" ::: "memory")
; #define PG8_BAR __builtin_amdgcn_s_barrier()
; #define PG8_SCHED __builtin_amdgcn_sched_barrier(0)
; template <class Epi, class Sched, bool ALIGN_EPI = false, bool SP2 = false>
; __device__ __forceinline__ void gemm_phase(PG8_LAS unsigned char* lds, const Gemm g, const Sched& S, const Epi& E, const int tid) {
;     ...
;         const char* nA = has_next ? (const char*)g.A + (size_t)nxt.pm * tstep : cA; const char* nB = has_next ? (const char*)g.Bt + (size_t)nxt.pn * tstep : cB;
;         for (int t = 0; t < nt; t += 2) {
;             const bool last = (t == nt - 2);
;             const char* a1 = cA + (size_t)(t + 1) * kstep;
;             const char* a2 = last ? nA : cA + (size_t)(t + 2) * kstep; const char* b2 = last ? nB : cB + (size_t)(t + 2) * kstep;
;             const char* a3 = a2 + kstep; const char* b3 = b2 + kstep;
;             if (last && has_next) S.a_ready(nxt);
;             if constexpr (SP2) {
;             PG8_LDB(B0, 0, 0); PG8_LDB(B1, 0, 1); PG8_SCHED; PG8_LDA(At, 0, 0); PG8_STAGE(PG8_SA(1, 1), a1 + hstep, voffA);
;             PG8_WAIT_V(8); PG8_WAIT_L(0); PG8_BAR; PG8_MMA(0, 0, At, B0); PG8_MMA(0, 1, At, B1); PG8_BAR; PG8_SCHED;
;             PG8_LDA(At, 0, 1); PG8_STAGE(PG8_SB(0, 0), b2, voffB); PG8_STAGE(PG8_SB(0, 1), b2 + hstep, voffB); PG8_STAGE(PG8_SA(0, 0), a2, voffA);
;             PG8_WAIT_V(8); PG8_WAIT_L(0); PG8_BAR; PG8_MMA(1, 0, At, B0); PG8_MMA(1, 1, At, B1); PG8_BAR; PG8_SCHED;
.LBB0_209:
	s_add_i32 s69, s10, 2
	s_add_u32 s74, s0, 0x80
	s_addc_u32 s11, s1, 0
	s_add_i32 s81, 0, 0x10000
	s_cmp_eq_u32 s39, s10
	s_cselect_b32 s11, s31, s11
	s_cselect_b32 s10, s30, s74
	s_cselect_b32 s77, s35, s13
	s_cselect_b32 s76, s34, s12
	s_add_i32 s74, 0, 0x14000
	v_add_u32_e32 v142, s81, v180
	v_add_u32_e32 v168, s74, v180
	s_waitcnt lgkmcnt(0)
	ds_read_b128 v[130:133], v142
	ds_read_b128 v[134:137], v142 offset:1024
	ds_read_b128 v[138:141], v142 offset:2048
	ds_read_b128 v[142:145], v142 offset:3072
	ds_read_b128 v[164:167], v168
	ds_read_b128 v[184:187], v168 offset:1024
	ds_read_b128 v[188:191], v168 offset:2048
	ds_read_b128 v[200:203], v168 offset:3072
	v_lshl_add_u64 v[168:169], s[0:1], 0, v[160:161]
	s_add_i32 m0, s78, 0xc000
	ds_read_b128 v[204:207], v181
	ds_read_b128 v[208:211], v181 offset:1024
	ds_read_b128 v[212:215], v181 offset:2048
	ds_read_b128 v[216:219], v181 offset:3072
	ds_read_b128 v[220:223], v181 offset:4096
	ds_read_b128 v[226:229], v181 offset:5120
	ds_read_b128 v[238:241], v181 offset:6144
	ds_read_b128 v[242:245], v181 offset:7168
	global_load_lds_dwordx4 v[168:169], off
	v_lshl_add_u64 v[168:169], s[0:1], 0, v[162:163]
	s_add_i32 m0, s78, 0xe000
	s_nop 0
	global_load_lds_dwordx4 v[168:169], off
	s_waitcnt vmcnt(8)
	s_waitcnt lgkmcnt(0)
	v_mfma_f32_16x16x32_bf16 v[126:129], v[130:133], v[204:207], v[126:129]
	v_mfma_f32_16x16x32_bf16 v[126:129], v[134:137], v[208:211], v[126:129]
	s_barrier
	s_setprio 1
	v_mfma_f32_16x16x32_bf16 v[122:125], v[138:141], v[204:207], v[122:125]
	v_mfma_f32_16x16x32_bf16 v[122:125], v[142:145], v[208:211], v[122:125]
	v_mfma_f32_16x16x32_bf16 v[110:113], v[130:133], v[212:215], v[110:113]
	v_mfma_f32_16x16x32_bf16 v[110:113], v[134:137], v[216:219], v[110:113]
	v_mfma_f32_16x16x32_bf16 v[106:109], v[138:141], v[212:215], v[106:109]
	v_mfma_f32_16x16x32_bf16 v[106:109], v[142:145], v[216:219], v[106:109]
	v_mfma_f32_16x16x32_bf16 v[94:97], v[130:133], v[220:223], v[94:97]
	v_mfma_f32_16x16x32_bf16 v[94:97], v[134:137], v[226:229], v[94:97]
	v_mfma_f32_16x16x32_bf16 v[90:93], v[138:141], v[220:223], v[90:93]
	v_mfma_f32_16x16x32_bf16 v[90:93], v[142:145], v[226:229], v[90:93]
	v_mfma_f32_16x16x32_bf16 v[78:81], v[130:133], v[238:241], v[78:81]
	v_mfma_f32_16x16x32_bf16 v[78:81], v[134:137], v[242:245], v[78:81]
	v_mfma_f32_16x16x32_bf16 v[74:77], v[138:141], v[238:241], v[74:77]
	v_mfma_f32_16x16x32_bf16 v[74:77], v[142:145], v[242:245], v[74:77]
	s_setprio 0
	s_setprio 1
	v_mfma_f32_16x16x32_bf16 v[118:121], v[164:167], v[204:207], v[118:121]
	v_mfma_f32_16x16x32_bf16 v[118:121], v[184:187], v[208:211], v[118:121]
	v_mfma_f32_16x16x32_bf16 v[114:117], v[188:191], v[204:207], v[114:117]
	v_mfma_f32_16x16x32_bf16 v[114:117], v[200:203], v[208:211], v[114:117]
	v_mfma_f32_16x16x32_bf16 v[102:105], v[164:167], v[212:215], v[102:105]
	v_mfma_f32_16x16x32_bf16 v[102:105], v[184:187], v[216:219], v[102:105]
	v_mfma_f32_16x16x32_bf16 v[98:101], v[188:191], v[212:215], v[98:101]
	v_mfma_f32_16x16x32_bf16 v[98:101], v[200:203], v[216:219], v[98:101]
	v_mfma_f32_16x16x32_bf16 v[86:89], v[164:167], v[220:223], v[86:89]
	v_mfma_f32_16x16x32_bf16 v[86:89], v[184:187], v[226:229], v[86:89]
	v_mfma_f32_16x16x32_bf16 v[82:85], v[188:191], v[220:223], v[82:85]
	v_mfma_f32_16x16x32_bf16 v[82:85], v[200:203], v[226:229], v[82:85]
	v_mfma_f32_16x16x32_bf16 v[70:73], v[164:167], v[238:241], v[70:73]
	v_mfma_f32_16x16x32_bf16 v[70:73], v[184:187], v[242:245], v[70:73]
	v_mfma_f32_16x16x32_bf16 v[66:69], v[188:191], v[238:241], v[66:69]
	v_mfma_f32_16x16x32_bf16 v[66:69], v[200:203], v[242:245], v[66:69]
	s_setprio 0
	s_barrier
	s_add_i32 s81, s81, s75
	v_lshl_add_u64 v[168:169], s[76:77], 0, v[148:149]
	s_mov_b32 m0, s81
	ds_read_b128 v[204:207], v181 offset:16384
	ds_read_b128 v[208:211], v181 offset:17408
	ds_read_b128 v[212:215], v181 offset:18432
	ds_read_b128 v[216:219], v181 offset:19456
	ds_read_b128 v[220:223], v181 offset:20480
	ds_read_b128 v[226:229], v181 offset:21504
	ds_read_b128 v[238:241], v181 offset:22528
	ds_read_b128 v[242:245], v181 offset:23552
	global_load_lds_dwordx4 v[168:169], off
	s_add_i32 m0, s81, 0x2000
	v_lshl_add_u64 v[246:247], s[76:77], 0, v[152:153]
	s_add_u32 s76, s76, s82
	s_addc_u32 s77, s77, 0
	s_add_i32 s74, s74, s75
	global_load_lds_dwordx4 v[246:247], off
	v_lshl_add_u64 v[248:249], s[76:77], 0, v[148:149]
	s_mov_b32 m0, s74
	v_lshl_add_u64 v[250:251], s[76:77], 0, v[152:153]
	global_load_lds_dwordx4 v[248:249], off
	s_add_i32 m0, s74, 0x2000
	v_lshl_add_u64 v[252:253], s[10:11], 0, v[146:147]
	global_load_lds_dwordx4 v[250:251], off
	s_mov_b32 m0, s78
	v_lshl_add_u64 v[194:195], s[10:11], 0, v[150:151]
	global_load_lds_dwordx4 v[252:253], off
	s_mov_b32 m0, s79
	s_nop 0
	global_load_lds_dwordx4 v[194:195], off
	s_waitcnt vmcnt(8)
	s_waitcnt lgkmcnt(0)
	v_mfma_f32_16x16x32_bf16 v[62:65], v[130:133], v[204:207], v[62:65]
	v_mfma_f32_16x16x32_bf16 v[62:65], v[134:137], v[208:211], v[62:65]
	s_barrier
; #define PG8_STAGE(bufoff, gbase, voff) do { _Pragma("unroll") for (int _i = 0; _i < 2; ++_i) \
;         __builtin_amdgcn_global_load_lds((const unsigned*)((const char*)(gbase) + (voff)[_i]), (PG8_LAS unsigned*)(lds + (bufoff) + ldsw + _i * 8192), 16, 0, 0); } while (0)
; #define PG8_LDA(dst, b, h) do { _Pragma("unroll") for (int m = 0; m < 4; ++m) _Pragma("unroll") for (int k = 0; k < 2; ++k) dst[m][k] = *(const PG8_LAS bf16x8*)(lds + PG8_SA(b, h) + aoff + m * 2048 + k * 1024); } while (0)
; #define PG8_LDB(dst, b, h) do { _Pragma("unroll") for (int n = 0; n < 2; ++n) _Pragma("unroll") for (int k = 0; k < 2; ++k) dst[n][k] = *(const PG8_LAS bf16x8*)(lds + PG8_SB(b, h) + boff + n * 2048 + k * 1024); } while (0)
; #define PG8_MMA(ai, bj, At, Bt) do { __builtin_amdgcn_s_setprio(1); _Pragma("unroll") for (int m = 0; m < 4; ++m) _Pragma("unroll") for (int n = 0; n < 2; ++n) _Pragma("unroll") for (int k = 0; k < 2; ++k) \
;         acc[ai][bj][m][n] = __builtin_amdgcn_mfma_f32_16x16x32_bf16(Bt[n][k], At[m][k], acc[ai][bj][m][n], 0, 0, 0); __builtin_amdgcn_s_setprio(0); } while (0)
; #define PG8_WAIT_V(n) asm volatile("s_waitcnt vmcnt(" #n ")" ::: "memory")
; #define PG8_WAIT_L(n) asm volatile("s_waitcnt lgkmcnt(" #n ")" ::: "memory")
; #define PG8_BAR __builtin_amdgcn_s_barrier()
; #define PG8_SCHED __builtin_amdgcn_sched_barrier(0)
; template <class Epi, class Sched, bool ALIGN_EPI = false, bool SP2 = false>
; __device__ __forceinline__ void gemm_phase(PG8_LAS unsigned char* lds, const Gemm g, const Sched& S, const Epi& E, const int tid) {
;     ...
;             PG8_WAIT_V(8); PG8_WAIT_L(0); PG8_BAR; PG8_MMA(1, 0, At, B0); PG8_MMA(1, 1, At, B1); PG8_BAR; PG8_SCHED;
;             PG8_LDB(B0, 1, 0); PG8_LDB(B1, 1, 1); PG8_SCHED; PG8_LDA(At, 1, 0); PG8_STAGE(PG8_SA(0, 1), a2 + hstep, voffA);
;             PG8_WAIT_V(8); PG8_WAIT_L(0); PG8_BAR; PG8_MMA(0, 0, At, B0); PG8_MMA(0, 1, At, B1); PG8_BAR; PG8_SCHED;
;             PG8_LDA(At, 1, 1); PG8_STAGE(PG8_SB(1, 0), b3, voffB); PG8_STAGE(PG8_SB(1, 1), b3 + hstep, voffB); PG8_STAGE(PG8_SA(1, 0), a3, voffA);
	s_setprio 1
	v_mfma_f32_16x16x32_bf16 v[58:61], v[138:141], v[204:207], v[58:61]
	v_mfma_f32_16x16x32_bf16 v[58:61], v[142:145], v[208:211], v[58:61]
	v_mfma_f32_16x16x32_bf16 v[46:49], v[130:133], v[212:215], v[46:49]
	v_mfma_f32_16x16x32_bf16 v[46:49], v[134:137], v[216:219], v[46:49]
	v_mfma_f32_16x16x32_bf16 v[42:45], v[138:141], v[212:215], v[42:45]
	v_mfma_f32_16x16x32_bf16 v[42:45], v[142:145], v[216:219], v[42:45]
	v_mfma_f32_16x16x32_bf16 v[30:33], v[130:133], v[220:223], v[30:33]
	v_mfma_f32_16x16x32_bf16 v[30:33], v[134:137], v[226:229], v[30:33]
	v_mfma_f32_16x16x32_bf16 v[26:29], v[138:141], v[220:223], v[26:29]
	v_mfma_f32_16x16x32_bf16 v[26:29], v[142:145], v[226:229], v[26:29]
	v_mfma_f32_16x16x32_bf16 v[14:17], v[130:133], v[238:241], v[14:17]
	v_mfma_f32_16x16x32_bf16 v[14:17], v[134:137], v[242:245], v[14:17]
	v_mfma_f32_16x16x32_bf16 v[10:13], v[138:141], v[238:241], v[10:13]
	v_mfma_f32_16x16x32_bf16 v[10:13], v[142:145], v[242:245], v[10:13]
	s_setprio 0
	s_setprio 1
	v_mfma_f32_16x16x32_bf16 v[54:57], v[164:167], v[204:207], v[54:57]
	v_mfma_f32_16x16x32_bf16 v[54:57], v[184:187], v[208:211], v[54:57]
	v_mfma_f32_16x16x32_bf16 v[50:53], v[188:191], v[204:207], v[50:53]
	v_mfma_f32_16x16x32_bf16 v[50:53], v[200:203], v[208:211], v[50:53]
	v_mfma_f32_16x16x32_bf16 v[38:41], v[164:167], v[212:215], v[38:41]
	v_mfma_f32_16x16x32_bf16 v[38:41], v[184:187], v[216:219], v[38:41]
	v_mfma_f32_16x16x32_bf16 v[34:37], v[188:191], v[212:215], v[34:37]
	v_mfma_f32_16x16x32_bf16 v[34:37], v[200:203], v[216:219], v[34:37]
	v_mfma_f32_16x16x32_bf16 v[22:25], v[164:167], v[220:223], v[22:25]
	v_mfma_f32_16x16x32_bf16 v[22:25], v[184:187], v[226:229], v[22:25]
	v_mfma_f32_16x16x32_bf16 v[18:21], v[188:191], v[220:223], v[18:21]
	v_mfma_f32_16x16x32_bf16 v[18:21], v[200:203], v[226:229], v[18:21]
	v_mfma_f32_16x16x32_bf16 v[6:9], v[164:167], v[238:241], v[6:9]
	v_mfma_f32_16x16x32_bf16 v[6:9], v[184:187], v[242:245], v[6:9]
	v_mfma_f32_16x16x32_bf16 v[2:5], v[188:191], v[238:241], v[2:5]
	v_mfma_f32_16x16x32_bf16 v[2:5], v[200:203], v[242:245], v[2:5]
	s_setprio 0
	s_barrier
	s_add_i32 s74, 0, 0x18000
	s_add_i32 s76, 0, 0x1c000
	v_add_u32_e32 v142, s74, v180
	v_add_u32_e32 v183, s76, v180
	ds_read_b128 v[130:133], v142
	ds_read_b128 v[134:137], v142 offset:1024
	ds_read_b128 v[138:141], v142 offset:2048
	ds_read_b128 v[142:145], v142 offset:3072
	ds_read_b128 v[164:167], v183
	ds_read_b128 v[184:187], v183 offset:1024
	ds_read_b128 v[188:191], v183 offset:2048
	ds_read_b128 v[200:203], v183 offset:3072
	s_add_u32 s10, s10, s82
	s_addc_u32 s11, s11, 0
	s_mov_b32 m0, s36
	v_lshl_add_u64 v[198:199], s[10:11], 0, v[146:147]
	ds_read_b128 v[204:207], v181 offset:32768
	ds_read_b128 v[208:211], v181 offset:33792
	ds_read_b128 v[212:215], v181 offset:34816
	ds_read_b128 v[216:219], v181 offset:35840
	ds_read_b128 v[220:223], v181 offset:36864
	ds_read_b128 v[226:229], v181 offset:37888
	ds_read_b128 v[238:241], v181 offset:38912
	ds_read_b128 v[242:245], v181 offset:39936
	global_load_lds_dwordx4 v[198:199], off
	v_lshl_add_u64 v[198:199], s[10:11], 0, v[150:151]
	s_mov_b32 m0, s37
	s_nop 0
	global_load_lds_dwordx4 v[198:199], off
	s_waitcnt vmcnt(8)
	s_waitcnt lgkmcnt(0)
	v_mfma_f32_16x16x32_bf16 v[126:129], v[130:133], v[204:207], v[126:129]
	v_mfma_f32_16x16x32_bf16 v[126:129], v[134:137], v[208:211], v[126:129]
	s_barrier
	s_setprio 1
	v_mfma_f32_16x16x32_bf16 v[122:125], v[138:141], v[204:207], v[122:125]
	v_mfma_f32_16x16x32_bf16 v[122:125], v[142:145], v[208:211], v[122:125]
	v_mfma_f32_16x16x32_bf16 v[110:113], v[130:133], v[212:215], v[110:113]
	v_mfma_f32_16x16x32_bf16 v[110:113], v[134:137], v[216:219], v[110:113]
	v_mfma_f32_16x16x32_bf16 v[106:109], v[138:141], v[212:215], v[106:109]
	v_mfma_f32_16x16x32_bf16 v[106:109], v[142:145], v[216:219], v[106:109]
	v_mfma_f32_16x16x32_bf16 v[94:97], v[130:133], v[220:223], v[94:97]
	v_mfma_f32_16x16x32_bf16 v[94:97], v[134:137], v[226:229], v[94:97]
	v_mfma_f32_16x16x32_bf16 v[90:93], v[138:141], v[220:223], v[90:93]
	v_mfma_f32_16x16x32_bf16 v[90:93], v[142:145], v[226:229], v[90:93]
	v_mfma_f32_16x16x32_bf16 v[78:81], v[130:133], v[238:241], v[78:81]
	v_mfma_f32_16x16x32_bf16 v[78:81], v[134:137], v[242:245], v[78:81]
	v_mfma_f32_16x16x32_bf16 v[74:77], v[138:141], v[238:241], v[74:77]
	v_mfma_f32_16x16x32_bf16 v[74:77], v[142:145], v[242:245], v[74:77]
	s_setprio 0
	s_setprio 1
	v_mfma_f32_16x16x32_bf16 v[118:121], v[164:167], v[204:207], v[118:121]
	v_mfma_f32_16x16x32_bf16 v[118:121], v[184:187], v[208:211], v[118:121]
	v_mfma_f32_16x16x32_bf16 v[114:117], v[188:191], v[204:207], v[114:117]
	v_mfma_f32_16x16x32_bf16 v[114:117], v[200:203], v[208:211], v[114:117]
	v_mfma_f32_16x16x32_bf16 v[102:105], v[164:167], v[212:215], v[102:105]
	v_mfma_f32_16x16x32_bf16 v[102:105], v[184:187], v[216:219], v[102:105]
	v_mfma_f32_16x16x32_bf16 v[98:101], v[188:191], v[212:215], v[98:101]
	v_mfma_f32_16x16x32_bf16 v[98:101], v[200:203], v[216:219], v[98:101]
	v_mfma_f32_16x16x32_bf16 v[86:89], v[164:167], v[220:223], v[86:89]
	v_mfma_f32_16x16x32_bf16 v[86:89], v[184:187], v[226:229], v[86:89]
	v_mfma_f32_16x16x32_bf16 v[82:85], v[188:191], v[220:223], v[82:85]
	v_mfma_f32_16x16x32_bf16 v[82:85], v[200:203], v[226:229], v[82:85]
	v_mfma_f32_16x16x32_bf16 v[70:73], v[164:167], v[238:241], v[70:73]
	v_mfma_f32_16x16x32_bf16 v[70:73], v[184:187], v[242:245], v[70:73]
	v_mfma_f32_16x16x32_bf16 v[66:69], v[188:191], v[238:241], v[66:69]
	v_mfma_f32_16x16x32_bf16 v[66:69], v[200:203], v[242:245], v[66:69]
	s_setprio 0
	s_barrier
; #define PG8_STAGE(bufoff, gbase, voff) do { _Pragma("unroll") for (int _i = 0; _i < 2; ++_i) \
;         __builtin_amdgcn_global_load_lds((const unsigned*)((const char*)(gbase) + (voff)[_i]), (PG8_LAS unsigned*)(lds + (bufoff) + ldsw + _i * 8192), 16, 0, 0); } while (0)
; #define PG8_LDA(dst, b, h) do { _Pragma("unroll") for (int m = 0; m < 4; ++m) _Pragma("unroll") for (int k = 0; k < 2; ++k) dst[m][k] = *(const PG8_LAS bf16x8*)(lds + PG8_SA(b, h) + aoff + m * 2048 + k * 1024); } while (0)
; #define PG8_BAR __builtin_amdgcn_s_barrier()
; template <class Epi, class Sched, bool ALIGN_EPI = false, bool SP2 = false>
; __device__ __forceinline__ void gemm_phase(PG8_LAS unsigned char* lds, const Gemm g, const Sched& S, const Epi& E, const int tid) {
;     ...
;             PG8_LDA(At, 1, 1); PG8_STAGE(PG8_SB(1, 0), b3, voffB); PG8_STAGE(PG8_SB(1, 1), b3 + hstep, voffB); PG8_STAGE(PG8_SA(1, 0), a3, voffA);
;             PG8_WAIT_V(8); PG8_WAIT_L(0); PG8_BAR; PG8_MMA(1, 0, At, B0); PG8_MMA(1, 1, At, B1); PG8_BAR; PG8_SCHED;
;             } else {
;             PG8_LDB(B0, 0, 0); PG8_SCHED; PG8_LDA(At, 0, 0); PG8_STAGE(PG8_SA(1, 1), a1 + hstep, voffA);
;             PG8_WAIT_L(8); PG8_BAR; PG8_WAIT_L(0); PG8_MMA(0, 0, At, B0); PG8_BAR; PG8_SCHED;
;             PG8_LDB(B1, 0, 1); PG8_STAGE(PG8_SB(0, 0), b2, voffB);
;             PG8_BAR; PG8_WAIT_L(0); PG8_MMA(0, 1, At, B1); PG8_BAR;
;             PG8_LDA(At, 0, 1); PG8_STAGE(PG8_SA(0, 0), a2, voffA);
;             PG8_BAR; PG8_WAIT_L(0); PG8_MMA(1, 0, At, B0); PG8_BAR; PG8_SCHED;
;             PG8_STAGE(PG8_SB(0, 1), b2 + hstep, voffB);
;             PG8_WAIT_V(6); PG8_BAR; PG8_MMA(1, 1, At, B1); PG8_BAR;
;             PG8_LDB(B0, 1, 0); PG8_SCHED; PG8_LDA(At, 1, 0); PG8_STAGE(PG8_SA(0, 1), a2 + hstep, voffA);
;             PG8_WAIT_L(8); PG8_BAR; PG8_WAIT_L(0); PG8_MMA(0, 0, At, B0); PG8_BAR; PG8_SCHED;
;             PG8_LDB(B1, 1, 1); PG8_STAGE(PG8_SB(1, 0), b3, voffB);
;             PG8_BAR; PG8_WAIT_L(0); PG8_MMA(0, 1, At, B1); PG8_BAR;
;             PG8_LDA(At, 1, 1); PG8_STAGE(PG8_SA(1, 0), a3, voffA);
;             PG8_BAR; PG8_WAIT_L(0); PG8_MMA(1, 0, At, B0); PG8_BAR; PG8_SCHED;
;             PG8_STAGE(PG8_SB(1, 1), b3 + hstep, voffB);
;             PG8_WAIT_V(6); PG8_BAR; PG8_MMA(1, 1, At, B1); PG8_BAR;
;             }
;         }
;         if constexpr (ALIGN_EPI) { if (wr == 0) PG8_BAR; }
	s_add_i32 s10, s74, s75
	v_lshl_add_u64 v[168:169], v[168:169], 0, s[90:91]
	s_mov_b32 m0, s10
	ds_read_b128 v[204:207], v181 offset:49152
	ds_read_b128 v[208:211], v181 offset:50176
	ds_read_b128 v[212:215], v181 offset:51200
	ds_read_b128 v[216:219], v181 offset:52224
	ds_read_b128 v[220:223], v181 offset:53248
	ds_read_b128 v[226:229], v181 offset:54272
	ds_read_b128 v[238:241], v181 offset:55296
	ds_read_b128 v[242:245], v181 offset:56320
	global_load_lds_dwordx4 v[168:169], off
	v_lshl_add_u64 v[168:169], v[246:247], 0, s[90:91]
	s_add_i32 m0, s10, 0x2000
	s_add_i32 s10, s76, s75
	global_load_lds_dwordx4 v[168:169], off
	v_lshl_add_u64 v[168:169], v[248:249], 0, s[90:91]
	s_mov_b32 m0, s10
	s_nop 0
	global_load_lds_dwordx4 v[168:169], off
	v_lshl_add_u64 v[168:169], v[250:251], 0, s[90:91]
	s_add_i32 m0, s10, 0x2000
	s_nop 0
	global_load_lds_dwordx4 v[168:169], off
	v_lshl_add_u64 v[168:169], v[252:253], 0, s[90:91]
	s_mov_b32 m0, s40
	s_nop 0
	global_load_lds_dwordx4 v[168:169], off
	v_lshl_add_u64 v[168:169], v[194:195], 0, s[90:91]
	s_mov_b32 m0, s41
	s_nop 0
	global_load_lds_dwordx4 v[168:169], off
	s_waitcnt vmcnt(8)
	s_waitcnt lgkmcnt(0)
	v_mfma_f32_16x16x32_bf16 v[62:65], v[130:133], v[204:207], v[62:65]
	v_mfma_f32_16x16x32_bf16 v[62:65], v[134:137], v[208:211], v[62:65]
	s_barrier
	s_setprio 1
	v_mfma_f32_16x16x32_bf16 v[58:61], v[138:141], v[204:207], v[58:61]
	v_mfma_f32_16x16x32_bf16 v[58:61], v[142:145], v[208:211], v[58:61]
	v_mfma_f32_16x16x32_bf16 v[46:49], v[130:133], v[212:215], v[46:49]
	v_mfma_f32_16x16x32_bf16 v[46:49], v[134:137], v[216:219], v[46:49]
	v_mfma_f32_16x16x32_bf16 v[42:45], v[138:141], v[212:215], v[42:45]
	v_mfma_f32_16x16x32_bf16 v[42:45], v[142:145], v[216:219], v[42:45]
	v_mfma_f32_16x16x32_bf16 v[30:33], v[130:133], v[220:223], v[30:33]
	v_mfma_f32_16x16x32_bf16 v[30:33], v[134:137], v[226:229], v[30:33]
	v_mfma_f32_16x16x32_bf16 v[26:29], v[138:141], v[220:223], v[26:29]
	v_mfma_f32_16x16x32_bf16 v[26:29], v[142:145], v[226:229], v[26:29]
	v_mfma_f32_16x16x32_bf16 v[14:17], v[130:133], v[238:241], v[14:17]
	v_mfma_f32_16x16x32_bf16 v[14:17], v[134:137], v[242:245], v[14:17]
	v_mfma_f32_16x16x32_bf16 v[10:13], v[138:141], v[238:241], v[10:13]
	v_mfma_f32_16x16x32_bf16 v[10:13], v[142:145], v[242:245], v[10:13]
	s_setprio 0
	s_setprio 1
	v_mfma_f32_16x16x32_bf16 v[54:57], v[164:167], v[204:207], v[54:57]
	v_mfma_f32_16x16x32_bf16 v[54:57], v[184:187], v[208:211], v[54:57]
	v_mfma_f32_16x16x32_bf16 v[50:53], v[188:191], v[204:207], v[50:53]
	v_mfma_f32_16x16x32_bf16 v[50:53], v[200:203], v[208:211], v[50:53]
	v_mfma_f32_16x16x32_bf16 v[38:41], v[164:167], v[212:215], v[38:41]
	v_mfma_f32_16x16x32_bf16 v[38:41], v[184:187], v[216:219], v[38:41]
	v_mfma_f32_16x16x32_bf16 v[34:37], v[188:191], v[212:215], v[34:37]
	v_mfma_f32_16x16x32_bf16 v[34:37], v[200:203], v[216:219], v[34:37]
	v_mfma_f32_16x16x32_bf16 v[22:25], v[164:167], v[220:223], v[22:25]
	v_mfma_f32_16x16x32_bf16 v[22:25], v[184:187], v[226:229], v[22:25]
	v_mfma_f32_16x16x32_bf16 v[18:21], v[188:191], v[220:223], v[18:21]
	v_mfma_f32_16x16x32_bf16 v[18:21], v[200:203], v[226:229], v[18:21]
	v_mfma_f32_16x16x32_bf16 v[6:9], v[164:167], v[238:241], v[6:9]
	v_mfma_f32_16x16x32_bf16 v[6:9], v[184:187], v[242:245], v[6:9]
	v_mfma_f32_16x16x32_bf16 v[2:5], v[188:191], v[238:241], v[2:5]
	v_mfma_f32_16x16x32_bf16 v[2:5], v[200:203], v[242:245], v[2:5]
	s_setprio 0
	s_barrier
	s_add_u32 s0, s0, 0x100
	s_addc_u32 s1, s1, 0
	s_add_u32 s12, s12, 0x100
	s_addc_u32 s13, s13, 0
	s_cmp_ge_u32 s69, s84
	s_mov_b32 s10, s69
	s_cbranch_scc0 .LBB0_209
	s_and_b64 vcc, exec, s[22:23]
	s_cbranch_vccz .LBB0_213
	s_barrier
	s_cmp_lt_i32 s3, 3
	s_mov_b64 s[0:1], -1
	s_cbranch_scc0 .LBB0_214
